# v52 + MLA steady step: the next tile's LDS-DMA issue blocks moved behind the first QK MFMAs (own SGPR temporaries), so the first MFMA issues right after the K fragment reads
# speedup vs baseline: 1.0106x; 1.0106x over previous
.LBB0_1476:
	s_mul_i32 s52, s49, 0x3000
	v_add_u32_e32 v66, s52, v182
	v_add_u32_e32 v67, v66, v184
	v_add_u32_e32 v66, v66, v189
	ds_read_b128 v[82:85], v67
	ds_read_b128 v[158:161], v67 offset:2048
	ds_read_b128 v[162:165], v66
	ds_read_b128 v[150:153], v66 offset:2048
	ds_read_b128 v[146:149], v67 offset:4096
	ds_read_b128 v[142:145], v67 offset:6144
	ds_read_b128 v[138:141], v66 offset:4096
	ds_read_b128 v[134:137], v66 offset:6144
	ds_read_b128 v[130:133], v67 offset:8192
	ds_read_b128 v[126:129], v67 offset:10240
	ds_read_b128 v[122:125], v66 offset:8192
	ds_read_b128 v[154:157], v66 offset:10240
	s_waitcnt lgkmcnt(11)
	v_mfma_f32_32x32x16_bf16 v[66:81], v[82:85], v[98:101], v[50:65]
	s_lshl_b32 s58, s49, 13
	s_waitcnt lgkmcnt(10)
	v_mfma_f32_32x32x16_bf16 v[82:97], v[158:161], v[98:101], v[50:65]
	v_add_u32_e32 v158, s58, v183
	s_add_u32 s26, s54, s24
	s_addc_u32 s27, s55, s25
	s_xor_b32 s57, s49, 1
	s_mul_i32 s56, s57, 0x3000
	s_add_i32 s51, s56, s38
	s_mov_b32 s98, m0
	s_mov_b32 m0, s51
	s_nop 0
	global_load_lds_dwordx4 v1, s[26:27]
	s_mov_b32 m0, s98
	s_and_b64 vcc, exec, s[8:9]
	s_cbranch_vccnz .LBB0_1478
	s_add_i32 s26, s56, s39
	s_mov_b32 s27, m0
	s_mov_b32 m0, s26
	s_nop 0
	global_load_lds_dwordx4 v180, s[22:23]
	s_mov_b32 m0, s27
.LBB0_1478:
	s_waitcnt lgkmcnt(9)
	v_mfma_f32_32x32x16_bf16 v[66:81], v[162:165], v[106:109], v[66:81]
	s_waitcnt lgkmcnt(8)
	v_mfma_f32_32x32x16_bf16 v[82:97], v[150:153], v[106:109], v[82:97]
	s_add_u32 s26, s0, s24
	s_addc_u32 s27, s53, s25
	s_lshl_b32 s51, s57, 13
	s_add_i32 s98, s51, s43
	s_mov_b32 s99, m0
	s_mov_b32 m0, s98
	s_nop 0
	global_load_lds_dwordx4 v181, s[26:27]
	s_mov_b32 m0, s99
	s_waitcnt lgkmcnt(7)
	v_mfma_f32_32x32x16_bf16 v[66:81], v[146:149], v[102:105], v[66:81]
	s_waitcnt lgkmcnt(6)
	v_mfma_f32_32x32x16_bf16 v[82:97], v[142:145], v[102:105], v[82:97]
	s_waitcnt lgkmcnt(5)
	v_mfma_f32_32x32x16_bf16 v[66:81], v[138:141], v[114:117], v[66:81]
	ds_read_b64_tr_b16 v[150:151], v158 offset:24576
	ds_read_b64_tr_b16 v[152:153], v158 offset:25088
	ds_read_b64_tr_b16 v[146:147], v158 offset:25600
	ds_read_b64_tr_b16 v[148:149], v158 offset:26112
	ds_read_b64_tr_b16 v[142:143], v158 offset:26624
	ds_read_b64_tr_b16 v[144:145], v158 offset:27136
	ds_read_b64_tr_b16 v[138:139], v158 offset:27648
	ds_read_b64_tr_b16 v[140:141], v158 offset:28160
	s_waitcnt lgkmcnt(12)
	v_mfma_f32_32x32x16_bf16 v[82:97], v[134:137], v[114:117], v[82:97]
	s_waitcnt lgkmcnt(11)
	v_mfma_f32_32x32x16_bf16 v[66:81], v[130:133], v[110:113], v[66:81]
	s_waitcnt lgkmcnt(10)
	v_mfma_f32_32x32x16_bf16 v[82:97], v[126:129], v[110:113], v[82:97]
	s_waitcnt lgkmcnt(9)
	v_mfma_f32_32x32x16_bf16 v[66:81], v[122:125], v[118:121], v[66:81]
	ds_read_b64_tr_b16 v[134:135], v158 offset:28672
	ds_read_b64_tr_b16 v[136:137], v158 offset:29184
	ds_read_b64_tr_b16 v[130:131], v158 offset:29696
	ds_read_b64_tr_b16 v[132:133], v158 offset:30208
	ds_read_b64_tr_b16 v[126:127], v158 offset:30720
	ds_read_b64_tr_b16 v[128:129], v158 offset:31232
	ds_read_b64_tr_b16 v[122:123], v158 offset:31744
	ds_read_b64_tr_b16 v[124:125], v158 offset:32256
	s_waitcnt lgkmcnt(14)
	v_mfma_f32_32x32x16_bf16 v[82:97], v[154:157], v[118:121], v[82:97]
	s_cmp_lg_u32 s101, 0
	s_cbranch_scc1 .Lmla2_fast
	s_nop 1
	v_max_f32_e32 v154, v67, v67
	v_max_f32_e32 v155, v66, v66
	v_max_f32_e32 v154, v155, v154
	s_nop 6
	v_max3_f32 v155, v68, v69, v83
	v_max3_f32 v154, v154, v82, v84
	v_max3_f32 v154, v154, v85, v70
	v_max3_f32 v155, v155, v72, v73
	v_max3_f32 v154, v154, v71, v86
	v_max3_f32 v155, v155, v88, v89
	v_max3_f32 v154, v154, v87, v74
	v_max3_f32 v155, v155, v76, v77
	v_max3_f32 v154, v154, v75, v90
	v_max3_f32 v155, v155, v92, v93
	v_max3_f32 v154, v154, v91, v78
	v_max3_f32 v155, v155, v80, v81
	v_max3_f32 v154, v154, v79, v94
	v_max3_f32 v155, v155, v96, v97
	v_max3_f32 v154, v154, v95, v155
	v_mov_b32_e32 v155, v154
	s_nop 1
	v_permlane32_swap_b32_e32 v154, v155
	v_max_f32_e32 v155, v155, v155
	v_max_f32_e32 v154, v154, v154
	v_max_f32_e32 v154, v154, v155
	v_cmp_lt_f32_e32 vcc, s47, v154
	s_cbranch_vccz .LBB0_1482
	v_max_f32_e32 v50, v154, v154
	v_max_f32_e32 v154, 0, v50
	v_exp_f32_e64 v155, -v154
	v_add_f32_e32 v171, v171, v154
	v_xor_b32_e32 v50, 0x80000000, v171
	v_mov_b32_e32 v51, v50
	v_mov_b32_e32 v52, v50
	v_mov_b32_e32 v53, v50
	v_mov_b32_e32 v54, v50
	v_mov_b32_e32 v55, v50
	v_mov_b32_e32 v56, v50
	v_mov_b32_e32 v57, v50
	v_mov_b32_e32 v58, v50
	v_mov_b32_e32 v59, v50
	v_mov_b32_e32 v60, v50
	v_mov_b32_e32 v61, v50
	v_mov_b32_e32 v62, v50
	v_mov_b32_e32 v63, v50
	v_mov_b32_e32 v64, v50
	v_mov_b32_e32 v65, v50
	s_and_saveexec_b64 s[26:27], s[6:7]
	ds_write_b32 v186, v155 offset:40960
	s_or_b64 exec, exec, s[26:27]
	v_add_u32_e32 v164, s42, v187
	ds_read_b128 v[156:159], v164 offset:41024
	ds_read_b128 v[160:163], v164 offset:41056
	ds_read_b128 v[196:199], v164 offset:40960
	ds_read_b128 v[200:203], v164 offset:40992
	v_pk_add_f32 v[66:67], v[66:67], v[154:155] op_sel_hi:[1,0] neg_lo:[0,1] neg_hi:[0,1]
	v_pk_add_f32 v[82:83], v[82:83], v[154:155] op_sel_hi:[1,0] neg_lo:[0,1] neg_hi:[0,1]
	v_pk_add_f32 v[68:69], v[68:69], v[154:155] op_sel_hi:[1,0] neg_lo:[0,1] neg_hi:[0,1]
	v_pk_add_f32 v[84:85], v[84:85], v[154:155] op_sel_hi:[1,0] neg_lo:[0,1] neg_hi:[0,1]
	v_pk_add_f32 v[70:71], v[70:71], v[154:155] op_sel_hi:[1,0] neg_lo:[0,1] neg_hi:[0,1]
	v_pk_add_f32 v[86:87], v[86:87], v[154:155] op_sel_hi:[1,0] neg_lo:[0,1] neg_hi:[0,1]
	v_pk_add_f32 v[72:73], v[72:73], v[154:155] op_sel_hi:[1,0] neg_lo:[0,1] neg_hi:[0,1]
	v_pk_add_f32 v[88:89], v[88:89], v[154:155] op_sel_hi:[1,0] neg_lo:[0,1] neg_hi:[0,1]
	v_pk_add_f32 v[74:75], v[74:75], v[154:155] op_sel_hi:[1,0] neg_lo:[0,1] neg_hi:[0,1]
	v_pk_add_f32 v[90:91], v[90:91], v[154:155] op_sel_hi:[1,0] neg_lo:[0,1] neg_hi:[0,1]
	v_pk_add_f32 v[76:77], v[76:77], v[154:155] op_sel_hi:[1,0] neg_lo:[0,1] neg_hi:[0,1]
	v_pk_add_f32 v[92:93], v[92:93], v[154:155] op_sel_hi:[1,0] neg_lo:[0,1] neg_hi:[0,1]
	v_pk_add_f32 v[78:79], v[78:79], v[154:155] op_sel_hi:[1,0] neg_lo:[0,1] neg_hi:[0,1]
	v_pk_add_f32 v[94:95], v[94:95], v[154:155] op_sel_hi:[1,0] neg_lo:[0,1] neg_hi:[0,1]
	v_pk_add_f32 v[80:81], v[80:81], v[154:155] op_sel_hi:[1,0] neg_lo:[0,1] neg_hi:[0,1]
	v_pk_add_f32 v[96:97], v[96:97], v[154:155] op_sel_hi:[1,0] neg_lo:[0,1] neg_hi:[0,1]
	v_mul_f32_e32 v173, v173, v155
	s_waitcnt lgkmcnt(2)
	v_pk_mul_f32 v[30:31], v[30:31], v[160:161]
	v_pk_mul_f32 v[26:27], v[26:27], v[156:157]
	s_waitcnt lgkmcnt(0)
	v_pk_mul_f32 v[22:23], v[22:23], v[200:201]
	v_pk_mul_f32 v[32:33], v[32:33], v[162:163]
	v_pk_mul_f32 v[28:29], v[28:29], v[158:159]
	v_pk_mul_f32 v[24:25], v[24:25], v[202:203]
	v_pk_mul_f32 v[20:21], v[20:21], v[198:199]
	v_pk_mul_f32 v[18:19], v[18:19], v[196:197]
	v_pk_mul_f32 v[46:47], v[46:47], v[160:161]
	v_pk_mul_f32 v[42:43], v[42:43], v[156:157]
	v_pk_mul_f32 v[38:39], v[38:39], v[200:201]
	v_pk_mul_f32 v[48:49], v[48:49], v[162:163]
	v_pk_mul_f32 v[44:45], v[44:45], v[158:159]
	v_pk_mul_f32 v[40:41], v[40:41], v[202:203]
	v_pk_mul_f32 v[36:37], v[36:37], v[198:199]
	v_pk_mul_f32 v[34:35], v[34:35], v[196:197]
